# v28 + MLA fast-path staging address code specialised per wave half (scalar branches instead of exec masks, -25 VALU per wave-iteration)
# baseline (speedup 1.0000x reference)
.Lmla_l0_negm_ok:
	s_nop 1
	s_waitcnt lgkmcnt(11)
	v_mfma_f32_32x32x16_bf16 v[64:79], v[2:5], v[92:95], v[124:139]
	ds_read_b128 v[2:5], v14 offset:21504
	s_waitcnt lgkmcnt(11)
	v_mfma_f32_32x32x16_bf16 v[64:79], v[6:9], v[96:99], v[64:79]
	ds_read_b128 v[6:9], v14 offset:21536
	s_waitcnt lgkmcnt(11)
	v_mfma_f32_32x32x16_bf16 v[64:79], v[10:13], v[100:103], v[64:79]
	ds_read_b128 v[10:13], v14 offset:21568
	s_waitcnt lgkmcnt(11)
	v_mfma_f32_32x32x16_bf16 v[64:79], v[140:143], v[104:107], v[64:79]
	ds_read_b128 v[140:143], v14 offset:21600
	s_waitcnt lgkmcnt(11)
	v_mfma_f32_32x32x16_bf16 v[64:79], v[234:237], v[116:119], v[64:79]
	ds_read_b128 v[234:237], v14 offset:21632
	s_waitcnt lgkmcnt(11)
	v_mfma_f32_32x32x16_bf16 v[64:79], v[240:243], v[120:123], v[64:79]
	ds_read_b128 v[240:243], v14 offset:21664
	s_waitcnt lgkmcnt(11)
	v_mfma_f32_32x32x16_bf16 v[48:63], v[202:205], v[92:95], v[124:139]
	s_waitcnt lgkmcnt(10)
	v_mfma_f32_32x32x16_bf16 v[48:63], v[206:209], v[96:99], v[48:63]
	s_waitcnt lgkmcnt(9)
	v_mfma_f32_32x32x16_bf16 v[48:63], v[210:213], v[100:103], v[48:63]
	s_waitcnt lgkmcnt(8)
	v_mfma_f32_32x32x16_bf16 v[48:63], v[214:217], v[104:107], v[48:63]
	s_waitcnt lgkmcnt(7)
	v_mfma_f32_32x32x16_bf16 v[48:63], v[218:221], v[116:119], v[48:63]
	s_waitcnt lgkmcnt(6)
	v_mfma_f32_32x32x16_bf16 v[48:63], v[222:225], v[120:123], v[48:63]
	v_exp_f32_e32 v64, v64
	v_exp_f32_e32 v65, v65
	s_waitcnt lgkmcnt(5)
	v_mfma_f32_32x32x16_bf16 v[202:217], v[2:5], v[92:95], v[124:139]
	ds_read_b128 v[2:5], v14 offset:28160
	v_exp_f32_e32 v66, v66
	v_exp_f32_e32 v67, v67
	v_exp_f32_e32 v68, v68
	v_exp_f32_e32 v69, v69
	v_exp_f32_e32 v70, v70
	s_waitcnt lgkmcnt(5)
	v_mfma_f32_32x32x16_bf16 v[202:217], v[6:9], v[96:99], v[202:217]
	ds_read_b128 v[6:9], v14 offset:28192
	v_exp_f32_e32 v71, v71
	v_pk_add_f32 v[246:247], v[64:65], v[66:67]
	v_exp_f32_e32 v72, v72
	v_exp_f32_e32 v73, v73
	v_exp_f32_e32 v74, v74
	s_waitcnt lgkmcnt(5)
	v_mfma_f32_32x32x16_bf16 v[202:217], v[10:13], v[100:103], v[202:217]
	ds_read_b128 v[10:13], v14 offset:28224
	v_exp_f32_e32 v75, v75
	v_pk_add_f32 v[248:249], v[68:69], v[70:71]
	v_exp_f32_e32 v76, v76
	v_exp_f32_e32 v77, v77
	v_pk_add_f32 v[246:247], v[246:247], v[72:73]
	s_waitcnt lgkmcnt(5)
	v_mfma_f32_32x32x16_bf16 v[202:217], v[140:143], v[104:107], v[202:217]
	ds_read_b128 v[140:143], v14 offset:28256
	v_exp_f32_e32 v78, v78
	v_exp_f32_e32 v79, v79
	v_pk_add_f32 v[248:249], v[248:249], v[74:75]
	v_exp_f32_e32 v48, v48
	v_exp_f32_e32 v49, v49
	s_waitcnt lgkmcnt(5)
	v_mfma_f32_32x32x16_bf16 v[202:217], v[234:237], v[116:119], v[202:217]
	ds_read_b128 v[234:237], v14 offset:28288
	v_pk_add_f32 v[246:247], v[246:247], v[76:77]
	v_exp_f32_e32 v50, v50
	v_exp_f32_e32 v51, v51
	v_pk_add_f32 v[248:249], v[248:249], v[78:79]
	v_exp_f32_e32 v52, v52
	s_waitcnt lgkmcnt(5)
	v_mfma_f32_32x32x16_bf16 v[202:217], v[240:243], v[120:123], v[202:217]
	ds_read_b128 v[240:243], v14 offset:28320
	v_exp_f32_e32 v53, v53
	v_pk_add_f32 v[246:247], v[246:247], v[48:49]
	v_exp_f32_e32 v54, v54
	v_exp_f32_e32 v55, v55
	v_pk_add_f32 v[248:249], v[248:249], v[50:51]
	s_waitcnt lgkmcnt(5)
	v_mfma_f32_32x32x16_bf16 v[218:233], v[2:5], v[92:95], v[124:139]
	ds_read_b64_tr_b16 v[2:3], v0 offset:13312
	ds_read_b64_tr_b16 v[4:5], v0 offset:13824
	v_exp_f32_e32 v56, v56
	v_exp_f32_e32 v57, v57
	v_pk_add_f32 v[246:247], v[246:247], v[52:53]
	v_exp_f32_e32 v58, v58
	v_exp_f32_e32 v59, v59
	s_waitcnt lgkmcnt(6)
	v_mfma_f32_32x32x16_bf16 v[218:233], v[6:9], v[96:99], v[218:233]
	ds_read_b64_tr_b16 v[6:7], v0 offset:17408
	ds_read_b64_tr_b16 v[8:9], v0 offset:17920
	v_pk_add_f32 v[248:249], v[248:249], v[54:55]
	v_exp_f32_e32 v60, v60
	v_exp_f32_e32 v61, v61
	v_pk_add_f32 v[246:247], v[246:247], v[56:57]
	v_exp_f32_e32 v62, v62
	s_waitcnt lgkmcnt(7)
	v_mfma_f32_32x32x16_bf16 v[218:233], v[10:13], v[100:103], v[218:233]
	ds_read_b64_tr_b16 v[10:11], v0 offset:14336
	ds_read_b64_tr_b16 v[12:13], v0 offset:14848
	v_exp_f32_e32 v63, v63
	v_pk_add_f32 v[248:249], v[248:249], v[58:59]
	v_pk_add_f32 v[246:247], v[246:247], v[60:61]
	v_pk_add_f32 v[248:249], v[248:249], v[62:63]
	v_pk_add_f32 v[246:247], v[246:247], v[248:249]
	s_waitcnt lgkmcnt(8)
	v_mfma_f32_32x32x16_bf16 v[218:233], v[140:143], v[104:107], v[218:233]
	ds_read_b64_tr_b16 v[140:141], v0 offset:18432
	ds_read_b64_tr_b16 v[142:143], v0 offset:18944
	v_add_f32_e32 v250, v246, v247
	v_cmp_ngt_f32_e32 vcc, 0x43800000, v250
	s_cbranch_vccnz .Lmla_l0_fbA
	v_add_f32_e32 v200, v200, v250
	v_cvt_pk_bf16_f32 v64, v64, v65
	v_cvt_pk_bf16_f32 v65, v66, v67
	s_waitcnt lgkmcnt(9)
	v_mfma_f32_32x32x16_bf16 v[218:233], v[234:237], v[116:119], v[218:233]
	ds_read_b64_tr_b16 v[234:235], v0 offset:15360
	ds_read_b64_tr_b16 v[236:237], v0 offset:15872
	v_cvt_pk_bf16_f32 v66, v68, v69
	v_cvt_pk_bf16_f32 v67, v70, v71
	v_cvt_pk_bf16_f32 v68, v72, v73
	v_cvt_pk_bf16_f32 v69, v74, v75
	v_cvt_pk_bf16_f32 v70, v76, v77
	s_waitcnt lgkmcnt(10)
	v_mfma_f32_32x32x16_bf16 v[218:233], v[240:243], v[120:123], v[218:233]
	ds_read_b64_tr_b16 v[240:241], v0 offset:19456
	ds_read_b64_tr_b16 v[242:243], v0 offset:19968
	v_cvt_pk_bf16_f32 v71, v78, v79
	v_cvt_pk_bf16_f32 v48, v48, v49
	v_cvt_pk_bf16_f32 v49, v50, v51
	v_cvt_pk_bf16_f32 v50, v52, v53
	v_cvt_pk_bf16_f32 v51, v54, v55
	v_cvt_pk_bf16_f32 v52, v56, v57
	v_cvt_pk_bf16_f32 v53, v58, v59
	v_cvt_pk_bf16_f32 v54, v60, v61
	v_cvt_pk_bf16_f32 v55, v62, v63
	v_exp_f32_e32 v202, v202
	v_exp_f32_e32 v203, v203
	s_waitcnt lgkmcnt(10)
	v_mfma_f32_32x32x16_bf16 v[32:47], v[2:5], v[64:67], v[32:47]
	v_exp_f32_e32 v204, v204
	v_exp_f32_e32 v205, v205
	v_exp_f32_e32 v206, v206
	v_exp_f32_e32 v207, v207
	v_exp_f32_e32 v208, v208
	s_waitcnt lgkmcnt(8)
	v_mfma_f32_32x32x16_bf16 v[16:31], v[6:9], v[64:67], v[16:31]
	v_exp_f32_e32 v209, v209
	v_pk_add_f32 v[246:247], v[202:203], v[204:205]
	v_exp_f32_e32 v210, v210
	v_exp_f32_e32 v211, v211
	v_exp_f32_e32 v212, v212
	s_waitcnt lgkmcnt(6)
	v_mfma_f32_32x32x16_bf16 v[32:47], v[10:13], v[68:71], v[32:47]
	ds_read_b64_tr_b16 v[2:3], v0 offset:16384
	ds_read_b64_tr_b16 v[4:5], v0 offset:16896
	v_exp_f32_e32 v213, v213
	v_pk_add_f32 v[248:249], v[206:207], v[208:209]
	v_exp_f32_e32 v214, v214
	v_exp_f32_e32 v215, v215
	v_pk_add_f32 v[246:247], v[246:247], v[210:211]
	s_waitcnt lgkmcnt(6)
	v_mfma_f32_32x32x16_bf16 v[16:31], v[140:143], v[68:71], v[16:31]
	ds_read_b64_tr_b16 v[6:7], v0 offset:20480
	ds_read_b64_tr_b16 v[8:9], v0 offset:20992
	v_exp_f32_e32 v216, v216
	v_exp_f32_e32 v217, v217
	v_pk_add_f32 v[248:249], v[248:249], v[212:213]
	v_exp_f32_e32 v218, v218
	v_exp_f32_e32 v219, v219
	s_waitcnt lgkmcnt(6)
	v_mfma_f32_32x32x16_bf16 v[32:47], v[234:237], v[48:51], v[32:47]
	ds_read_b64_tr_b16 v[72:73], v0 offset:34816
	ds_read_b64_tr_b16 v[74:75], v0 offset:35328
	v_pk_add_f32 v[246:247], v[246:247], v[214:215]
	v_exp_f32_e32 v220, v220
	v_exp_f32_e32 v221, v221
	v_pk_add_f32 v[248:249], v[248:249], v[216:217]
	v_exp_f32_e32 v222, v222
	s_waitcnt lgkmcnt(6)
	v_mfma_f32_32x32x16_bf16 v[16:31], v[240:243], v[48:51], v[16:31]
	ds_read_b64_tr_b16 v[76:77], v0 offset:38912
	ds_read_b64_tr_b16 v[78:79], v0 offset:39424
	v_exp_f32_e32 v223, v223
	v_pk_add_f32 v[246:247], v[246:247], v[218:219]
	v_exp_f32_e32 v224, v224
	v_exp_f32_e32 v225, v225
	v_pk_add_f32 v[248:249], v[248:249], v[220:221]
	s_waitcnt lgkmcnt(6)
	v_mfma_f32_32x32x16_bf16 v[32:47], v[2:5], v[52:55], v[32:47]
	ds_read_b64_tr_b16 v[56:57], v0 offset:35840
	ds_read_b64_tr_b16 v[58:59], v0 offset:36352
	v_exp_f32_e32 v226, v226
	v_exp_f32_e32 v227, v227
	v_pk_add_f32 v[246:247], v[246:247], v[222:223]
	v_exp_f32_e32 v228, v228
	v_exp_f32_e32 v229, v229
	s_waitcnt lgkmcnt(6)
	v_mfma_f32_32x32x16_bf16 v[16:31], v[6:9], v[52:55], v[16:31]
	ds_read_b64_tr_b16 v[60:61], v0 offset:39936
	ds_read_b64_tr_b16 v[62:63], v0 offset:40448
	v_pk_add_f32 v[248:249], v[248:249], v[224:225]
	v_exp_f32_e32 v230, v230
	v_exp_f32_e32 v231, v231
	v_pk_add_f32 v[246:247], v[246:247], v[226:227]
	v_exp_f32_e32 v232, v232
	v_exp_f32_e32 v233, v233
	v_pk_add_f32 v[248:249], v[248:249], v[228:229]
	v_pk_add_f32 v[246:247], v[246:247], v[230:231]
	v_pk_add_f32 v[248:249], v[248:249], v[232:233]
	v_pk_add_f32 v[246:247], v[246:247], v[248:249]
	v_add_f32_e32 v250, v246, v247
	v_cmp_ngt_f32_e32 vcc, 0x43800000, v250
	s_cbranch_vccnz .Lmla_l0_fbB
	v_add_f32_e32 v200, v200, v250
	v_cvt_pk_bf16_f32 v202, v202, v203
	v_cvt_pk_bf16_f32 v203, v204, v205
	v_cvt_pk_bf16_f32 v204, v206, v207
	v_cvt_pk_bf16_f32 v205, v208, v209
	v_cvt_pk_bf16_f32 v206, v210, v211
	v_cvt_pk_bf16_f32 v207, v212, v213
	v_cvt_pk_bf16_f32 v208, v214, v215
	v_cvt_pk_bf16_f32 v209, v216, v217
	v_cvt_pk_bf16_f32 v218, v218, v219
	v_cvt_pk_bf16_f32 v219, v220, v221
	v_cvt_pk_bf16_f32 v220, v222, v223
	v_cvt_pk_bf16_f32 v221, v224, v225
	v_cvt_pk_bf16_f32 v222, v226, v227
	v_cvt_pk_bf16_f32 v223, v228, v229
	v_cvt_pk_bf16_f32 v224, v230, v231
	v_cvt_pk_bf16_f32 v225, v232, v233
	s_waitcnt lgkmcnt(6)
	v_mfma_f32_32x32x16_bf16 v[32:47], v[72:75], v[202:205], v[32:47]
	ds_read_b64_tr_b16 v[10:11], v0 offset:36864
	ds_read_b64_tr_b16 v[12:13], v0 offset:37376
	s_waitcnt vmcnt(0)
	s_xor_b32 s16, s18, 1
	s_mul_i32 s16, s16, 0xa800
	v_add_u32_e32 v254, s16, v170
	v_add3_u32 v254, v254, v192, v193
	ds_write_b128 v254, v[80:83]
	s_cmp_eq_u64 s[4:5], 0
	s_cbranch_scc0 .Lmla_l0_pw_hi
	v_add_u32_e32 v252, s16, v172
	v_add3_u32 v252, v252, v194, v195
	v_add_u32_e32 v253, s16, v174
	v_add_u32_e32 v253, v253, v149
	v_add3_u32 v253, v253, v175, v169
	v_add_u32_e32 v253, 0x1c00, v253
	s_branch .Lmla_l0_pw_join
.Lmla_l0_pw_hi:
	v_add_u32_e32 v252, s16, v172
	v_add_u32_e32 v252, v252, v149
	v_add3_u32 v252, v252, v173, v169
	v_add_u32_e32 v252, 0x1c00, v252
	v_add_u32_e32 v253, s16, v174
	v_add3_u32 v253, v253, v196, v197
.Lmla_l0_pw_join:
	ds_write_b128 v252, v[84:87]
	ds_write_b128 v253, v[88:91]
	v_add_u32_e32 v254, s16, v176
	v_add3_u32 v254, v254, v198, v199
	ds_write_b128 v254, v[108:111]
	v_add_u32_e32 v254, s16, v178
	v_add_u32_e32 v254, v254, v149
	v_add3_u32 v254, v254, v179, v169
	v_add_u32_e32 v254, 0x1c00, v254
	ds_write_b128 v254, v[112:115]
	s_waitcnt lgkmcnt(11)
	v_mfma_f32_32x32x16_bf16 v[16:31], v[76:79], v[202:205], v[16:31]
	ds_read_b64_tr_b16 v[140:141], v0 offset:40960
	ds_read_b64_tr_b16 v[142:143], v0 offset:41472
	s_waitcnt lgkmcnt(11)
	v_mfma_f32_32x32x16_bf16 v[32:47], v[56:59], v[206:209], v[32:47]
	ds_read_b64_tr_b16 v[234:235], v0 offset:37888
	ds_read_b64_tr_b16 v[236:237], v0 offset:38400
	s_waitcnt lgkmcnt(11)
	v_mfma_f32_32x32x16_bf16 v[16:31], v[60:63], v[206:209], v[16:31]
	ds_read_b64_tr_b16 v[240:241], v0 offset:41984
	ds_read_b64_tr_b16 v[242:243], v0 offset:42496
	s_waitcnt lgkmcnt(11)
	v_mfma_f32_32x32x16_bf16 v[32:47], v[10:13], v[218:221], v[32:47]
	s_waitcnt lgkmcnt(4)
	v_mfma_f32_32x32x16_bf16 v[16:31], v[140:143], v[218:221], v[16:31]
	s_add_i32 s0, s19, 0xc0
	s_cmp_le_i32 s0, s67
	s_cbranch_scc0 .Lmla_l0_noload
	s_add_u32 s16, s12, 0x30000
	s_addc_u32 s17, s13, 0
	s_add_i32 s0, s76, 1
	s_lshl_b32 s0, s0, 1
	v_mov_b32_e32 v255, 0
	v_lshl_add_u64 v[252:253], v[158:159], 0, s[16:17]
	global_load_dwordx4 v[80:83], v[252:253], off
	s_cmp_eq_u64 s[4:5], 0
	s_cbranch_scc0 .Lmla_l0_pi_hi
	v_lshl_add_u64 v[252:253], v[156:157], 0, s[16:17]
	global_load_dwordx4 v[84:87], v[252:253], off
	v_or_b32_e32 v254, s0, v188
	v_lshl_add_u32 v254, v254, 6, v166
	v_lshlrev_b64 v[252:253], 10, v[254:255]
	v_lshl_add_u64 v[252:253], v[144:145], 0, v[252:253]
	global_load_dwordx4 v[88:91], v[252:253], off
	s_branch .Lmla_l0_pi_join
.Lmla_l0_pi_hi:
	v_or_b32_e32 v254, s0, v187
	v_lshl_add_u32 v254, v254, 6, v165
	v_lshlrev_b64 v[252:253], 10, v[254:255]
	v_lshl_add_u64 v[252:253], v[144:145], 0, v[252:253]
	global_load_dwordx4 v[84:87], v[252:253], off
	v_lshl_add_u64 v[252:253], v[154:155], 0, s[16:17]
	global_load_dwordx4 v[88:91], v[252:253], off
.Lmla_l0_pi_join:
	v_lshl_add_u64 v[252:253], v[152:153], 0, s[16:17]
	global_load_dwordx4 v[108:111], v[252:253], off
	v_or_b32_e32 v254, s0, v190
	v_lshl_add_u32 v254, v254, 6, v168
	v_lshlrev_b64 v[252:253], 10, v[254:255]
	v_lshl_add_u64 v[252:253], v[144:145], 0, v[252:253]
	global_load_dwordx4 v[112:115], v[252:253], off

.Lmla_l1_pw_join:
	ds_write_b128 v252, v[84:87]
	ds_write_b128 v253, v[88:91]
	v_add_u32_e32 v254, s16, v176
	v_add3_u32 v254, v254, v198, v199
	ds_write_b128 v254, v[108:111]
	v_add_u32_e32 v254, s16, v178
	v_add_u32_e32 v254, v254, v149
	v_add3_u32 v254, v254, v179, v169
	v_add_u32_e32 v254, 0x1c00, v254
	ds_write_b128 v254, v[112:115]
	s_waitcnt lgkmcnt(11)
	v_mfma_f32_32x32x16_bf16 v[16:31], v[76:79], v[202:205], v[16:31]
	ds_read_b64_tr_b16 v[140:141], v0 offset:40960
	ds_read_b64_tr_b16 v[142:143], v0 offset:41472
	s_waitcnt lgkmcnt(11)
	v_mfma_f32_32x32x16_bf16 v[32:47], v[56:59], v[206:209], v[32:47]
	ds_read_b64_tr_b16 v[234:235], v0 offset:37888
	ds_read_b64_tr_b16 v[236:237], v0 offset:38400
	s_waitcnt lgkmcnt(11)
	v_mfma_f32_32x32x16_bf16 v[16:31], v[60:63], v[206:209], v[16:31]
	ds_read_b64_tr_b16 v[240:241], v0 offset:41984
	ds_read_b64_tr_b16 v[242:243], v0 offset:42496
	s_waitcnt lgkmcnt(11)
	v_mfma_f32_32x32x16_bf16 v[32:47], v[10:13], v[218:221], v[32:47]
	s_waitcnt lgkmcnt(4)
	v_mfma_f32_32x32x16_bf16 v[16:31], v[140:143], v[218:221], v[16:31]
	s_add_i32 s0, s19, 0xc0
	s_cmp_le_i32 s0, s84
	s_cbranch_scc0 .Lmla_l1_noload
	s_add_u32 s16, s12, 0x30000
	s_addc_u32 s17, s13, 0
	s_add_i32 s0, s94, 1
	s_lshl_b32 s0, s0, 1
	v_mov_b32_e32 v255, 0
	v_lshl_add_u64 v[252:253], v[158:159], 0, s[16:17]
	global_load_dwordx4 v[80:83], v[252:253], off
	s_cmp_eq_u64 s[4:5], 0
	s_cbranch_scc0 .Lmla_l1_pi_hi
	v_lshl_add_u64 v[252:253], v[156:157], 0, s[16:17]
	global_load_dwordx4 v[84:87], v[252:253], off
	v_or_b32_e32 v254, s0, v188
	v_lshl_add_u32 v254, v254, 6, v166
	v_lshlrev_b64 v[252:253], 10, v[254:255]
	v_lshl_add_u64 v[252:253], v[144:145], 0, v[252:253]
	global_load_dwordx4 v[88:91], v[252:253], off
	s_branch .Lmla_l1_pi_join
